# v27 + rotated k-loops (barrier ahead of the previous slice's last MFMA group, DMA interleaved) for M2/E2/E4/O5
# speedup vs baseline: 1.0137x; 1.0137x over previous
.LBB0_1222:
	s_waitcnt vmcnt(0)
	ds_write_b32 v2, v246
	v_ashrrev_i32_e32 v103, 6, v100
	v_lshrrev_b32_e32 v0, 30, v103
	v_add_u32_e32 v0, v103, v0
	v_ashrrev_i32_e32 v10, 2, v0
	v_mul_i32_i24_e32 v0, 4, v10
	v_ashrrev_i32_e32 v6, 3, v100
	v_sub_u32_e32 v11, v103, v0
	v_lshrrev_b32_e32 v13, 4, v100
	v_add_u32_e32 v0, s4, v6
	v_xor_b32_e32 v7, v13, v100
	v_ashrrev_i32_e32 v1, 31, v0
	v_lshlrev_b64 v[0:1], 11, v[0:1]
	v_lshlrev_b32_e32 v7, 4, v7
	v_lshlrev_b32_e32 v109, 4, v100
	s_and_b32 s8, s2, 0xffffff00
	v_lshl_add_u64 v[4:5], s[46:47], 0, v[0:1]
	v_and_b32_e32 v128, 0x70, v7
	v_readfirstlane_b32 s2, v109
	v_add_u32_e32 v14, 0x2000, v109
	v_lshl_add_u64 v[4:5], v[4:5], 0, v[128:129]
	s_mov_b32 m0, s2
	s_mov_b64 s[10:11], 0x20000
	v_readfirstlane_b32 s2, v14
	ds_write_b32 v2, v3 offset:2048
	v_lshl_add_u64 v[2:3], v[4:5], 0, s[10:11]
	s_mov_b32 m0, s2
	s_mov_b64 s[12:13], 0x40000
	v_lshl_add_u64 v[2:3], v[4:5], 0, s[12:13]
	v_add_u32_e32 v4, 0x4000, v109
	v_add_u32_e32 v6, s8, v6
	v_readfirstlane_b32 s2, v4
	v_ashrrev_i32_e32 v7, 31, v6
	s_mov_b32 m0, s2
	v_lshlrev_b64 v[6:7], 11, v[6:7]
	v_add_u32_e32 v2, 0x6000, v109
	v_lshl_add_u64 v[8:9], s[56:57], 0, v[6:7]
	v_readfirstlane_b32 s2, v2
	v_add_u32_e32 v4, 0x8000, v109
	v_lshl_add_u64 v[8:9], v[8:9], 0, v[128:129]
	s_mov_b32 m0, s2
	v_readfirstlane_b32 s2, v4
	v_add_u32_e32 v4, 0xa000, v109
	v_lshl_add_u64 v[2:3], v[8:9], 0, s[10:11]
	s_mov_b32 m0, s2
	v_readfirstlane_b32 s2, v4
	v_lshl_add_u64 v[2:3], v[8:9], 0, s[12:13]
	s_mov_b32 m0, s2
	s_mov_b64 s[2:3], 0x60000
	v_add_u32_e32 v4, 0xc000, v109
	v_lshl_add_u64 v[2:3], v[8:9], 0, s[2:3]
	v_readfirstlane_b32 s2, v4
	s_mov_b32 m0, s2
	v_and_b32_e32 v102, 31, v100
	v_lshlrev_b32_e32 v105, 6, v11
	v_or_b32_e32 v3, v105, v102
	v_mul_i32_i24_e32 v106, 0x60, v10
	v_bfe_u32 v12, v100, 5, 1
	v_lshrrev_b32_e32 v104, 1, v100
	v_lshlrev_b32_e32 v112, 7, v3
	v_or_b32_e32 v3, v106, v102
	v_bfe_u32 v2, v100, 1, 3
	v_lshlrev_b32_e32 v113, 7, v3
	v_bitop3_b32 v3, v12, v104, 7 bitop3:0x78
	v_lshlrev_b32_e32 v111, 4, v3
	v_bitop3_b32 v3, v12, v2, 2 bitop3:0x36
	v_lshlrev_b32_e32 v110, 4, v3
	v_bitop3_b32 v3, v12, v2, 4 bitop3:0x36
	v_bitop3_b32 v2, v12, v2, 6 bitop3:0x36
	v_lshlrev_b32_e32 v107, 4, v2
	v_bitop3_b32 v2, v13, 7, v100 bitop3:0x48
	v_lshlrev_b32_e32 v2, 4, v2
	v_or_b32_e32 v6, v6, v2
	v_or_b32_e32 v0, v0, v2
	v_and_b32_e32 v101, 63, v100
	v_lshlrev_b32_e32 v108, 4, v3
	v_add_u32_e32 v114, 0x6000, v112
	v_lshl_add_u64 v[96:97], s[58:59], 0, v[6:7]
	v_lshl_add_u64 v[98:99], s[14:15], 0, v[0:1]
	s_mov_b32 s7, 0
	s_mov_b64 s[2:3], 0
	v_mov_b32_e32 v33, v32
	v_mov_b32_e32 v34, v32
	v_mov_b32_e32 v35, v32
	v_mov_b32_e32 v36, v32
	v_mov_b32_e32 v37, v32
	v_mov_b32_e32 v38, v32
	v_mov_b32_e32 v39, v32
	v_mov_b32_e32 v40, v32
	v_mov_b32_e32 v41, v32
	v_mov_b32_e32 v42, v32
	v_mov_b32_e32 v43, v32
	v_mov_b32_e32 v44, v32
	v_mov_b32_e32 v45, v32
	v_mov_b32_e32 v46, v32
	v_mov_b32_e32 v47, v32
	v_mov_b32_e32 v64, v32
	v_mov_b32_e32 v65, v32
	v_mov_b32_e32 v66, v32
	v_mov_b32_e32 v67, v32
	v_mov_b32_e32 v68, v32
	v_mov_b32_e32 v69, v32
	v_mov_b32_e32 v70, v32
	v_mov_b32_e32 v71, v32
	v_mov_b32_e32 v72, v32
	v_mov_b32_e32 v73, v32
	v_mov_b32_e32 v74, v32
	v_mov_b32_e32 v75, v32
	v_mov_b32_e32 v76, v32
	v_mov_b32_e32 v77, v32
	v_mov_b32_e32 v78, v32
	v_mov_b32_e32 v79, v32
	v_mov_b32_e32 v0, v32
	v_mov_b32_e32 v1, v32
	v_mov_b32_e32 v2, v32
	v_mov_b32_e32 v3, v32
	v_mov_b32_e32 v4, v32
	v_mov_b32_e32 v5, v32
	v_mov_b32_e32 v6, v32
	v_mov_b32_e32 v7, v32
	v_mov_b32_e32 v8, v32
	v_mov_b32_e32 v9, v32
	v_mov_b32_e32 v10, v32
	v_mov_b32_e32 v11, v32
	v_mov_b32_e32 v12, v32
	v_mov_b32_e32 v13, v32
	v_mov_b32_e32 v14, v32
	v_mov_b32_e32 v15, v32
	v_mov_b32_e32 v80, v32
	v_mov_b32_e32 v81, v32
	v_mov_b32_e32 v82, v32
	v_mov_b32_e32 v83, v32
	v_mov_b32_e32 v84, v32
	v_mov_b32_e32 v85, v32
	v_mov_b32_e32 v86, v32
	v_mov_b32_e32 v87, v32
	v_mov_b32_e32 v88, v32
	v_mov_b32_e32 v89, v32
	v_mov_b32_e32 v90, v32
	v_mov_b32_e32 v91, v32
	v_mov_b32_e32 v92, v32
	v_mov_b32_e32 v93, v32
	v_mov_b32_e32 v94, v32
	v_mov_b32_e32 v95, v32
	v_mov_b32_e32 v48, v32
	v_mov_b32_e32 v49, v32
	v_mov_b32_e32 v50, v32
	v_mov_b32_e32 v51, v32
	v_mov_b32_e32 v52, v32
	v_mov_b32_e32 v53, v32
	v_mov_b32_e32 v54, v32
	v_mov_b32_e32 v55, v32
	v_mov_b32_e32 v56, v32
	v_mov_b32_e32 v57, v32
	v_mov_b32_e32 v58, v32
	v_mov_b32_e32 v59, v32
	v_mov_b32_e32 v60, v32
	v_mov_b32_e32 v61, v32
	v_mov_b32_e32 v62, v32
	v_mov_b32_e32 v63, v32
	v_mov_b32_e32 v16, v32
	v_mov_b32_e32 v17, v32
	v_mov_b32_e32 v18, v32
	v_mov_b32_e32 v19, v32
	v_mov_b32_e32 v20, v32
	v_mov_b32_e32 v21, v32
	v_mov_b32_e32 v22, v32
	v_mov_b32_e32 v23, v32
	v_mov_b32_e32 v24, v32
	v_mov_b32_e32 v25, v32
	v_mov_b32_e32 v26, v32
	v_mov_b32_e32 v27, v32
	v_mov_b32_e32 v28, v32
	v_mov_b32_e32 v29, v32
	v_mov_b32_e32 v30, v32
	v_mov_b32_e32 v31, v32
	s_mov_b64 s[12:13], 0x8794080
	s_mov_b64 s[16:17], 0x87b4080
	s_mov_b64 s[18:19], 0x87d4080
	v_add_u32_e32 v243, s4, v106
	v_lshrrev_b32_e32 v244, 4, v101
	v_or_b32_e32 v243, v243, v244
	v_and_b32_e32 v244, 15, v100
	v_add_u32_e32 v245, s8, v105
	v_lshl_or_b32 v244, v244, 2, v245
	v_lshlrev_b32_e32 v243, 12, v243
	v_lshl_add_u32 v243, v244, 2, v243
	global_load_dwordx4 v[198:201], v243, s[42:43]
	v_add_u32_e32 v243, 0x4000, v243
	global_load_dwordx4 v[202:205], v243, s[42:43]
	v_add_u32_e32 v243, 0x4000, v243
	global_load_dwordx4 v[206:209], v243, s[42:43]
	v_add_u32_e32 v243, 0x4000, v243
	global_load_dwordx4 v[210:213], v243, s[42:43]
	v_add_u32_e32 v243, 0x4000, v243
	global_load_dwordx4 v[214:217], v243, s[42:43]
	v_add_u32_e32 v243, 0x4000, v243
	global_load_dwordx4 v[218:221], v243, s[42:43]
	v_add_u32_e32 v243, 0x4000, v243
	global_load_dwordx4 v[222:225], v243, s[42:43]
	v_add_u32_e32 v243, 0x4000, v243
	global_load_dwordx4 v[226:229], v243, s[42:43]
	s_add_i32 s9, s7, 1
	s_bitcmp1_b32 s9, 0
	s_cselect_b32 s10, 0xe000, 0
	v_add_u32_e32 v246, s10, v109
	s_bitcmp1_b32 s7, 0
	s_cselect_b32 s10, 0xe000, 0
	v_add_u32_e32 v153, s10, v114
	v_add_u32_e32 v154, s10, v113
	s_waitcnt vmcnt(0) lgkmcnt(0)
	s_barrier
	v_add_u32_e32 v181, v153, v111
	ds_read_b128 v[116:119], v181 offset:0x0
	ds_read_b128 v[120:123], v181 offset:0x1000
	v_add_u32_e32 v181, v154, v111
	ds_read_b128 v[124:127], v181 offset:0x0
	ds_read_b128 v[130:133], v181 offset:0x1000
	ds_read_b128 v[134:137], v181 offset:0x2000
	v_add_u32_e32 v181, v153, v110
	ds_read_b128 v[144:147], v181 offset:0x0
	ds_read_b128 v[148:151], v181 offset:0x1000
	v_add_u32_e32 v181, v154, v110
	ds_read_b128 v[182:185], v181 offset:0x0
	ds_read_b128 v[186:189], v181 offset:0x1000
	ds_read_b128 v[190:193], v181 offset:0x2000
	s_waitcnt lgkmcnt(5)
	v_mfma_f32_32x32x16_bf16 v[64:79], v[116:119], v[124:127], v[64:79]
	v_mfma_f32_32x32x16_bf16 v[32:47], v[116:119], v[130:133], v[32:47]
	v_lshl_add_u64 v[244:245], v[98:99], 0, s[2:3]
	v_lshl_add_u64 v[244:245], v[244:245], 0, s[12:13]
	v_readfirstlane_b32 s10, v246
	s_mov_b32 m0, s10
	s_nop 0
	global_load_lds_dwordx4 v[244:245], off
	v_mfma_f32_32x32x16_bf16 v[0:15], v[116:119], v[134:137], v[0:15]
	v_mfma_f32_32x32x16_bf16 v[80:95], v[120:123], v[124:127], v[80:95]
	v_add_u32_e32 v243, 0x2000, v246
	v_lshl_add_u64 v[244:245], v[98:99], 0, s[2:3]
	v_lshl_add_u64 v[244:245], v[244:245], 0, s[16:17]
	v_readfirstlane_b32 s10, v243
	s_mov_b32 m0, s10
	s_nop 0
	global_load_lds_dwordx4 v[244:245], off
	v_mfma_f32_32x32x16_bf16 v[48:63], v[120:123], v[130:133], v[48:63]
	v_mfma_f32_32x32x16_bf16 v[16:31], v[120:123], v[134:137], v[16:31]
	v_add_u32_e32 v243, 0x4000, v246
	v_lshl_add_u64 v[244:245], v[98:99], 0, s[2:3]
	v_lshl_add_u64 v[244:245], v[244:245], 0, s[18:19]
	v_readfirstlane_b32 s10, v243
	s_mov_b32 m0, s10
	s_nop 0
	global_load_lds_dwordx4 v[244:245], off
	v_add_u32_e32 v181, v153, v108
	ds_read_b128 v[116:119], v181 offset:0x0
	ds_read_b128 v[120:123], v181 offset:0x1000
	v_add_u32_e32 v181, v154, v108
	ds_read_b128 v[124:127], v181 offset:0x0
	ds_read_b128 v[130:133], v181 offset:0x1000
	ds_read_b128 v[134:137], v181 offset:0x2000
	s_waitcnt lgkmcnt(5)
	v_mfma_f32_32x32x16_bf16 v[64:79], v[144:147], v[182:185], v[64:79]
	v_mfma_f32_32x32x16_bf16 v[32:47], v[144:147], v[186:189], v[32:47]
	v_add_u32_e32 v243, 0x6000, v246
	s_mov_b64 s[10:11], 0x5f14080
	v_lshl_add_u64 v[244:245], v[96:97], 0, s[2:3]
	v_lshl_add_u64 v[244:245], v[244:245], 0, s[10:11]
	v_readfirstlane_b32 s10, v243
	s_mov_b32 m0, s10
	s_nop 0
	global_load_lds_dwordx4 v[244:245], off
	v_mfma_f32_32x32x16_bf16 v[0:15], v[144:147], v[190:193], v[0:15]
	v_mfma_f32_32x32x16_bf16 v[80:95], v[148:151], v[182:185], v[80:95]
	v_add_u32_e32 v243, 0x8000, v246
	s_mov_b64 s[10:11], 0x5f34080
	v_lshl_add_u64 v[244:245], v[96:97], 0, s[2:3]
	v_lshl_add_u64 v[244:245], v[244:245], 0, s[10:11]
	v_readfirstlane_b32 s10, v243
	s_mov_b32 m0, s10
	s_nop 0
	global_load_lds_dwordx4 v[244:245], off
	v_mfma_f32_32x32x16_bf16 v[48:63], v[148:151], v[186:189], v[48:63]
	v_mfma_f32_32x32x16_bf16 v[16:31], v[148:151], v[190:193], v[16:31]
	v_add_u32_e32 v243, 0xa000, v246
	s_mov_b64 s[10:11], 0x5f54080
	v_lshl_add_u64 v[244:245], v[96:97], 0, s[2:3]
	v_lshl_add_u64 v[244:245], v[244:245], 0, s[10:11]
	v_readfirstlane_b32 s10, v243
	s_mov_b32 m0, s10
	s_nop 0
	global_load_lds_dwordx4 v[244:245], off
	v_add_u32_e32 v181, v153, v107
	ds_read_b128 v[144:147], v181 offset:0x0
	ds_read_b128 v[148:151], v181 offset:0x1000
	v_add_u32_e32 v181, v154, v107
	ds_read_b128 v[182:185], v181 offset:0x0
	ds_read_b128 v[186:189], v181 offset:0x1000
	ds_read_b128 v[190:193], v181 offset:0x2000
	s_waitcnt lgkmcnt(5)
	v_mfma_f32_32x32x16_bf16 v[64:79], v[116:119], v[124:127], v[64:79]
	v_mfma_f32_32x32x16_bf16 v[32:47], v[116:119], v[130:133], v[32:47]
	v_add_u32_e32 v243, 0xc000, v246
	s_mov_b64 s[10:11], 0x5f74080
	v_lshl_add_u64 v[244:245], v[96:97], 0, s[2:3]
	v_lshl_add_u64 v[244:245], v[244:245], 0, s[10:11]
	v_readfirstlane_b32 s10, v243
	s_mov_b32 m0, s10
	s_nop 0
	global_load_lds_dwordx4 v[244:245], off
	v_mfma_f32_32x32x16_bf16 v[0:15], v[116:119], v[134:137], v[0:15]
	v_mfma_f32_32x32x16_bf16 v[80:95], v[120:123], v[124:127], v[80:95]
	v_mfma_f32_32x32x16_bf16 v[48:63], v[120:123], v[130:133], v[48:63]
	v_mfma_f32_32x32x16_bf16 v[16:31], v[120:123], v[134:137], v[16:31]
	s_waitcnt lgkmcnt(0)
	s_add_u32 s2, s2, 0x80
	s_addc_u32 s3, s3, 0
	s_mov_b32 s7, s9
.LBB0_1223:
	s_add_i32 s9, s7, 1
	s_bitcmp1_b32 s9, 0
	s_cselect_b32 s10, 0xe000, 0
	v_add_u32_e32 v246, s10, v109
	s_bitcmp1_b32 s7, 0
	s_cselect_b32 s10, 0xe000, 0
	v_add_u32_e32 v153, s10, v114
	v_add_u32_e32 v154, s10, v113
	s_waitcnt vmcnt(0) lgkmcnt(0)
	s_barrier
	v_add_u32_e32 v181, v153, v111
	ds_read_b128 v[116:119], v181 offset:0x0
	ds_read_b128 v[120:123], v181 offset:0x1000
	v_add_u32_e32 v181, v154, v111
	ds_read_b128 v[124:127], v181 offset:0x0
	ds_read_b128 v[130:133], v181 offset:0x1000
	ds_read_b128 v[134:137], v181 offset:0x2000
	v_mfma_f32_32x32x16_bf16 v[64:79], v[144:147], v[182:185], v[64:79]
	v_mfma_f32_32x32x16_bf16 v[32:47], v[144:147], v[186:189], v[32:47]
	v_lshl_add_u64 v[244:245], v[98:99], 0, s[2:3]
	v_lshl_add_u64 v[244:245], v[244:245], 0, s[12:13]
	v_readfirstlane_b32 s10, v246
	s_mov_b32 m0, s10
	s_nop 0
	global_load_lds_dwordx4 v[244:245], off
	v_mfma_f32_32x32x16_bf16 v[0:15], v[144:147], v[190:193], v[0:15]
	v_mfma_f32_32x32x16_bf16 v[80:95], v[148:151], v[182:185], v[80:95]
	v_add_u32_e32 v243, 0x2000, v246
	v_lshl_add_u64 v[244:245], v[98:99], 0, s[2:3]
	v_lshl_add_u64 v[244:245], v[244:245], 0, s[16:17]
	v_readfirstlane_b32 s10, v243
	s_mov_b32 m0, s10
	s_nop 0
	global_load_lds_dwordx4 v[244:245], off
	v_mfma_f32_32x32x16_bf16 v[48:63], v[148:151], v[186:189], v[48:63]
	v_mfma_f32_32x32x16_bf16 v[16:31], v[148:151], v[190:193], v[16:31]
	v_add_u32_e32 v243, 0x4000, v246
	v_lshl_add_u64 v[244:245], v[98:99], 0, s[2:3]
	v_lshl_add_u64 v[244:245], v[244:245], 0, s[18:19]
	v_readfirstlane_b32 s10, v243
	s_mov_b32 m0, s10
	s_nop 0
	global_load_lds_dwordx4 v[244:245], off
	v_add_u32_e32 v181, v153, v110
	ds_read_b128 v[144:147], v181 offset:0x0
	ds_read_b128 v[148:151], v181 offset:0x1000
	v_add_u32_e32 v181, v154, v110
	ds_read_b128 v[182:185], v181 offset:0x0
	ds_read_b128 v[186:189], v181 offset:0x1000
	ds_read_b128 v[190:193], v181 offset:0x2000
	s_waitcnt lgkmcnt(5)
	v_mfma_f32_32x32x16_bf16 v[64:79], v[116:119], v[124:127], v[64:79]
	v_mfma_f32_32x32x16_bf16 v[32:47], v[116:119], v[130:133], v[32:47]
	v_add_u32_e32 v243, 0x6000, v246
	s_mov_b64 s[10:11], 0x5f14080
	v_lshl_add_u64 v[244:245], v[96:97], 0, s[2:3]
	v_lshl_add_u64 v[244:245], v[244:245], 0, s[10:11]
	v_readfirstlane_b32 s10, v243
	s_mov_b32 m0, s10
	s_nop 0
	global_load_lds_dwordx4 v[244:245], off
	v_mfma_f32_32x32x16_bf16 v[0:15], v[116:119], v[134:137], v[0:15]
	v_mfma_f32_32x32x16_bf16 v[80:95], v[120:123], v[124:127], v[80:95]
	v_add_u32_e32 v243, 0x8000, v246
	s_mov_b64 s[10:11], 0x5f34080
	v_lshl_add_u64 v[244:245], v[96:97], 0, s[2:3]
	v_lshl_add_u64 v[244:245], v[244:245], 0, s[10:11]
	v_readfirstlane_b32 s10, v243
	s_mov_b32 m0, s10
	s_nop 0
	global_load_lds_dwordx4 v[244:245], off
	v_mfma_f32_32x32x16_bf16 v[48:63], v[120:123], v[130:133], v[48:63]
	v_mfma_f32_32x32x16_bf16 v[16:31], v[120:123], v[134:137], v[16:31]
	v_add_u32_e32 v243, 0xa000, v246
	s_mov_b64 s[10:11], 0x5f54080
	v_lshl_add_u64 v[244:245], v[96:97], 0, s[2:3]
	v_lshl_add_u64 v[244:245], v[244:245], 0, s[10:11]
	v_readfirstlane_b32 s10, v243
	s_mov_b32 m0, s10
	s_nop 0
	global_load_lds_dwordx4 v[244:245], off
	v_add_u32_e32 v181, v153, v108
	ds_read_b128 v[116:119], v181 offset:0x0
	ds_read_b128 v[120:123], v181 offset:0x1000
	v_add_u32_e32 v181, v154, v108
	ds_read_b128 v[124:127], v181 offset:0x0
	ds_read_b128 v[130:133], v181 offset:0x1000
	ds_read_b128 v[134:137], v181 offset:0x2000
	s_waitcnt lgkmcnt(5)
	v_mfma_f32_32x32x16_bf16 v[64:79], v[144:147], v[182:185], v[64:79]
	v_mfma_f32_32x32x16_bf16 v[32:47], v[144:147], v[186:189], v[32:47]
	v_add_u32_e32 v243, 0xc000, v246
	s_mov_b64 s[10:11], 0x5f74080
	v_lshl_add_u64 v[244:245], v[96:97], 0, s[2:3]
	v_lshl_add_u64 v[244:245], v[244:245], 0, s[10:11]
	v_readfirstlane_b32 s10, v243
	s_mov_b32 m0, s10
	s_nop 0
	global_load_lds_dwordx4 v[244:245], off
	v_mfma_f32_32x32x16_bf16 v[0:15], v[144:147], v[190:193], v[0:15]
	v_mfma_f32_32x32x16_bf16 v[80:95], v[148:151], v[182:185], v[80:95]
	v_mfma_f32_32x32x16_bf16 v[48:63], v[148:151], v[186:189], v[48:63]
	v_mfma_f32_32x32x16_bf16 v[16:31], v[148:151], v[190:193], v[16:31]
	v_add_u32_e32 v181, v153, v107
	ds_read_b128 v[144:147], v181 offset:0x0
	ds_read_b128 v[148:151], v181 offset:0x1000
	v_add_u32_e32 v181, v154, v107
	ds_read_b128 v[182:185], v181 offset:0x0
	ds_read_b128 v[186:189], v181 offset:0x1000
	ds_read_b128 v[190:193], v181 offset:0x2000
	s_waitcnt lgkmcnt(5)
	v_mfma_f32_32x32x16_bf16 v[64:79], v[116:119], v[124:127], v[64:79]
	v_mfma_f32_32x32x16_bf16 v[32:47], v[116:119], v[130:133], v[32:47]
	v_mfma_f32_32x32x16_bf16 v[0:15], v[116:119], v[134:137], v[0:15]
	v_mfma_f32_32x32x16_bf16 v[80:95], v[120:123], v[124:127], v[80:95]
	v_mfma_f32_32x32x16_bf16 v[48:63], v[120:123], v[130:133], v[48:63]
	v_mfma_f32_32x32x16_bf16 v[16:31], v[120:123], v[134:137], v[16:31]
	s_waitcnt lgkmcnt(0)
	s_add_u32 s2, s2, 0x80
	s_addc_u32 s3, s3, 0
	s_mov_b32 s7, s9
	s_cmpk_lg_i32 s2, 0x780
	s_cbranch_scc1 .LBB0_1223
	s_bitcmp1_b32 s7, 0
	s_cselect_b32 s10, 0xe000, 0
	v_add_u32_e32 v153, s10, v114
	v_add_u32_e32 v154, s10, v113
	s_waitcnt vmcnt(0) lgkmcnt(0)
	s_barrier
	v_add_u32_e32 v181, v153, v111
	ds_read_b128 v[116:119], v181 offset:0x0
	ds_read_b128 v[120:123], v181 offset:0x1000
	v_add_u32_e32 v181, v154, v111
	ds_read_b128 v[124:127], v181 offset:0x0
	ds_read_b128 v[130:133], v181 offset:0x1000
	ds_read_b128 v[134:137], v181 offset:0x2000
	v_mfma_f32_32x32x16_bf16 v[64:79], v[144:147], v[182:185], v[64:79]
	v_mfma_f32_32x32x16_bf16 v[32:47], v[144:147], v[186:189], v[32:47]
	v_mfma_f32_32x32x16_bf16 v[0:15], v[144:147], v[190:193], v[0:15]
	v_mfma_f32_32x32x16_bf16 v[80:95], v[148:151], v[182:185], v[80:95]
	v_mfma_f32_32x32x16_bf16 v[48:63], v[148:151], v[186:189], v[48:63]
	v_mfma_f32_32x32x16_bf16 v[16:31], v[148:151], v[190:193], v[16:31]
	v_add_u32_e32 v181, v153, v110
	ds_read_b128 v[144:147], v181 offset:0x0
	ds_read_b128 v[148:151], v181 offset:0x1000
	v_add_u32_e32 v181, v154, v110
	ds_read_b128 v[182:185], v181 offset:0x0
	ds_read_b128 v[186:189], v181 offset:0x1000
	ds_read_b128 v[190:193], v181 offset:0x2000
	s_waitcnt lgkmcnt(5)
	v_mfma_f32_32x32x16_bf16 v[64:79], v[116:119], v[124:127], v[64:79]
	v_mfma_f32_32x32x16_bf16 v[32:47], v[116:119], v[130:133], v[32:47]
	v_mfma_f32_32x32x16_bf16 v[0:15], v[116:119], v[134:137], v[0:15]
	v_mfma_f32_32x32x16_bf16 v[80:95], v[120:123], v[124:127], v[80:95]
	v_mfma_f32_32x32x16_bf16 v[48:63], v[120:123], v[130:133], v[48:63]
	v_mfma_f32_32x32x16_bf16 v[16:31], v[120:123], v[134:137], v[16:31]
	v_add_u32_e32 v181, v153, v108
	ds_read_b128 v[116:119], v181 offset:0x0
	ds_read_b128 v[120:123], v181 offset:0x1000
	v_add_u32_e32 v181, v154, v108
	ds_read_b128 v[124:127], v181 offset:0x0
	ds_read_b128 v[130:133], v181 offset:0x1000
	ds_read_b128 v[134:137], v181 offset:0x2000
	s_waitcnt lgkmcnt(5)
	v_mfma_f32_32x32x16_bf16 v[64:79], v[144:147], v[182:185], v[64:79]
	v_mfma_f32_32x32x16_bf16 v[32:47], v[144:147], v[186:189], v[32:47]
	v_mfma_f32_32x32x16_bf16 v[0:15], v[144:147], v[190:193], v[0:15]
	v_mfma_f32_32x32x16_bf16 v[80:95], v[148:151], v[182:185], v[80:95]
	v_mfma_f32_32x32x16_bf16 v[48:63], v[148:151], v[186:189], v[48:63]
	v_mfma_f32_32x32x16_bf16 v[16:31], v[148:151], v[190:193], v[16:31]
	v_add_u32_e32 v181, v153, v107
	ds_read_b128 v[144:147], v181 offset:0x0
	ds_read_b128 v[148:151], v181 offset:0x1000
	v_add_u32_e32 v181, v154, v107
	ds_read_b128 v[182:185], v181 offset:0x0
	ds_read_b128 v[186:189], v181 offset:0x1000
	ds_read_b128 v[190:193], v181 offset:0x2000
	s_waitcnt lgkmcnt(5)
	v_mfma_f32_32x32x16_bf16 v[64:79], v[116:119], v[124:127], v[64:79]
	v_mfma_f32_32x32x16_bf16 v[32:47], v[116:119], v[130:133], v[32:47]
	v_mfma_f32_32x32x16_bf16 v[0:15], v[116:119], v[134:137], v[0:15]
	v_mfma_f32_32x32x16_bf16 v[80:95], v[120:123], v[124:127], v[80:95]
	v_mfma_f32_32x32x16_bf16 v[48:63], v[120:123], v[130:133], v[48:63]
	v_mfma_f32_32x32x16_bf16 v[16:31], v[120:123], v[134:137], v[16:31]
	s_waitcnt lgkmcnt(0)
	v_mfma_f32_32x32x16_bf16 v[64:79], v[144:147], v[182:185], v[64:79]
	v_mfma_f32_32x32x16_bf16 v[32:47], v[144:147], v[186:189], v[32:47]
	v_mfma_f32_32x32x16_bf16 v[0:15], v[144:147], v[190:193], v[0:15]
	v_mfma_f32_32x32x16_bf16 v[80:95], v[148:151], v[182:185], v[80:95]
	v_mfma_f32_32x32x16_bf16 v[48:63], v[148:151], v[186:189], v[48:63]
	v_mfma_f32_32x32x16_bf16 v[16:31], v[148:151], v[190:193], v[16:31]
	v_add_u32_e32 v96, s4, v106
	v_lshrrev_b32_e32 v128, 4, v101
	v_and_b32_e32 v112, 15, v100
	v_or_b32_e32 v100, v96, v128
	v_add_u32_e32 v105, s8, v105
	v_ashrrev_i32_e32 v101, 31, v100
	v_lshl_or_b32 v98, v112, 2, v105
	v_lshlrev_b64 v[106:107], 12, v[100:101]
	v_ashrrev_i32_e32 v99, 31, v98
	v_lshl_add_u64 v[106:107], s[42:43], 0, v[106:107]
	v_lshl_add_u64 v[110:111], v[98:99], 2, v[106:107]
	s_barrier
	v_add_co_u32_e32 v182, vcc, 0x20000, v110
	s_nop 1
	v_addc_co_u32_e32 v183, vcc, 0, v111, vcc
	global_load_dwordx4 v[184:187], v[182:183], off
	v_add_co_u32_e32 v182, vcc, 0x4000, v182
	s_nop 1
	v_addc_co_u32_e32 v183, vcc, 0, v183, vcc
	global_load_dwordx4 v[188:191], v[182:183], off
	v_add_co_u32_e32 v182, vcc, 0x4000, v182
	s_nop 1
	v_addc_co_u32_e32 v183, vcc, 0, v183, vcc
	global_load_dwordx4 v[192:195], v[182:183], off
	v_add_co_u32_e32 v182, vcc, 0x4000, v182
	s_nop 1
	v_addc_co_u32_e32 v183, vcc, 0, v183, vcc
	global_load_dwordx4 v[116:119], v[182:183], off
	v_add_co_u32_e32 v182, vcc, 0x4000, v182
	s_nop 1
	v_addc_co_u32_e32 v183, vcc, 0, v183, vcc
	global_load_dwordx4 v[120:123], v[182:183], off
	v_add_co_u32_e32 v182, vcc, 0x4000, v182
	s_nop 1
	v_addc_co_u32_e32 v183, vcc, 0, v183, vcc
	global_load_dwordx4 v[124:127], v[182:183], off
	v_add_co_u32_e32 v182, vcc, 0x4000, v182
	s_nop 1
	v_addc_co_u32_e32 v183, vcc, 0, v183, vcc
	global_load_dwordx4 v[130:133], v[182:183], off
	v_add_co_u32_e32 v182, vcc, 0x4000, v182
	s_nop 1
	v_addc_co_u32_e32 v183, vcc, 0, v183, vcc
	global_load_dwordx4 v[134:137], v[182:183], off
	s_movk_i32 s2, 0x2400
	s_cmp_lt_i32 s5, 22
	v_mul_lo_u32 v97, v103, s2
	s_cselect_b64 s[2:3], -1, 0
	s_cmp_gt_i32 s5, 21
	s_movk_i32 s5, 0x110
	v_and_b32_e32 v103, 16, v104
	v_mad_u32_u24 v104, v102, s5, v97
	v_add_u32_e32 v113, 0xfffff000, v96
	v_cndmask_b32_e64 v102, 0, 1, s[2:3]
	s_cselect_b64 s[2:3], -1, 0
	s_add_i32 s7, s4, 0xfffff000
	v_add_u32_e32 v104, v104, v103
	ds_write_b128 v104, v[64:67]
	ds_write_b128 v104, v[68:71] offset:32
	ds_write_b128 v104, v[72:75] offset:64
	ds_write_b128 v104, v[76:79] offset:96
	ds_write_b128 v104, v[80:83] offset:128
	ds_write_b128 v104, v[84:87] offset:160
	ds_write_b128 v104, v[88:91] offset:192
	ds_write_b128 v104, v[92:95] offset:224
	v_xor_b32_e32 v64, s7, v113
	s_movk_i32 s4, 0x400
	v_lshl_or_b32 v97, v112, 4, v97
	v_cmp_gt_u32_e32 vcc, s4, v64
	v_mad_u32_u24 v115, v128, s5, v97
	s_and_b64 s[4:5], s[2:3], vcc
	v_cndmask_b32_e64 v71, 0, 1, s[4:5]
	s_movk_i32 s4, 0x1000
	v_cmp_gt_i32_e32 vcc, s4, v100
	v_subrev_u32_e32 v114, s8, v98
	v_lshl_add_u32 v103, v114, 2, v167
	v_cndmask_b32_e32 v64, v71, v102, vcc
	v_and_b32_e32 v64, 1, v64
	v_cmp_eq_u32_e32 vcc, 1, v64
	v_ashrrev_i32_e32 v68, 6, v105
	s_mov_b32 s4, 0xc000
	v_cndmask_b32_e64 v64, v171, 0, vcc
	v_add_u32_e32 v70, v103, v64
	ds_read_b128 v[64:67], v115
	ds_read_b128 v[72:75], v70
	v_cmp_eq_u32_e64 s[40:41], 0, v112
	v_mad_i64_i32 v[68:69], s[4:5], v68, s4, 0
	s_and_b64 vcc, exec, s[0:1]
	s_waitcnt lgkmcnt(0)
	v_pk_fma_f32 v[66:67], v[66:67], v[74:75], v[200:201]
	v_pk_fma_f32 v[64:65], v[64:65], v[72:73], v[198:199]
	global_store_dwordx4 v[110:111], v[64:67], off
	s_cbranch_vccnz .LBB0_1228
	ds_read_b128 v[72:75], v70 offset:2048
	v_lshlrev_b64 v[76:77], 10, v[100:101]
	v_lshl_add_u64 v[76:77], v[76:77], 1, s[44:45]
	v_lshl_add_u64 v[76:77], v[98:99], 1, v[76:77]
	s_waitcnt lgkmcnt(0)
	v_pk_mul_f32 v[72:73], v[64:65], v[72:73]
	v_pk_mul_f32 v[64:65], v[64:65], v[64:65]
	v_pk_mul_f32 v[74:75], v[66:67], v[74:75]
	v_pk_mul_f32 v[66:67], v[66:67], v[66:67]
	v_add_f32_e32 v64, v64, v65
	v_add_f32_e32 v64, v66, v64
	v_add_f32_e32 v64, v67, v64
	v_cvt_pk_bf16_f32 v72, v72, v73
	v_cvt_pk_bf16_f32 v73, v74, v75
	v_add_f32_dpp v64, v64, v64 quad_perm:[1,0,3,2] row_mask:0xf bank_mask:0xf bound_ctrl:1
	global_store_dwordx2 v[76:77], v[72:73], off
	s_nop 0
	v_add_f32_dpp v64, v64, v64 quad_perm:[2,3,0,1] row_mask:0xf bank_mask:0xf bound_ctrl:1
	s_nop 1
	v_add_f32_dpp v64, v64, v64 row_half_mirror row_mask:0xf bank_mask:0xf bound_ctrl:1
	s_nop 1
	v_mov_b32_dpp v65, v64 row_mirror row_mask:0xf bank_mask:0xf bound_ctrl:1
	s_and_saveexec_b64 s[4:5], s[40:41]
	s_cbranch_execz .LBB0_1227
	v_lshl_add_u64 v[66:67], s[48:49], 0, v[68:69]
	v_lshl_add_u64 v[66:67], v[100:101], 2, v[66:67]
	v_add_f32_e32 v64, v64, v65
	global_store_dword v[66:67], v64, off
